# cache-policy hints: nt on the once-streamed f32 weight / x / mem loads of the conversion code (prologue + deferred slices), sc1 write-through on the converted bf16 weight stores
# speedup vs baseline: 1.0436x; 1.0436x over previous
.LBB0_44:
	v_add_u32_e32 v6, s12, v65
	v_ashrrev_i32_e32 v7, 31, v6
	v_mul_lo_u32 v1, s22, v7
	v_mul_lo_u32 v4, s23, v6
	v_mad_u64_u32 v[2:3], s[20:21], s22, v6, 0
	v_add3_u32 v3, v3, v1, v4
	v_lshl_add_u64 v[2:3], v[2:3], 2, s[6:7]
	s_ashr_i32 s25, s24, 31
	v_and_b32_e32 v66, 28, v0
	v_lshl_add_u64 v[2:3], s[24:25], 2, v[2:3]
	v_mov_b32_e32 v33, 0
	v_lshlrev_b32_e32 v32, 2, v66
	v_lshl_add_u64 v[4:5], v[2:3], 0, v[32:33]
	global_load_dwordx4 v[0:3], v[4:5], off nt
	s_cmp_lg_u64 s[4:5], 0
	v_mov_b32_e32 v68, 1.0
	s_cselect_b64 s[20:21], -1, 0
	s_cmp_eq_u64 s[4:5], 0
	v_lshl_add_u64 v[34:35], v[6:7], 2, s[4:5]
	v_mov_b32_e32 v70, 1.0
	s_cbranch_scc1 .LBB0_46
	global_load_dword v70, v[34:35], off
.LBB0_46:
	s_lshl_b64 s[6:7], s[22:23], 5
	v_lshl_add_u64 v[8:9], v[4:5], 0, s[6:7]
	global_load_dwordx4 v[4:7], v[8:9], off nt
	v_cndmask_b32_e64 v10, 0, 1, s[20:21]
	v_cmp_ne_u32_e64 s[4:5], 1, v10
	s_andn2_b64 vcc, exec, s[20:21]
	s_cbranch_vccnz .LBB0_48
	global_load_dword v68, v[34:35], off offset:32
.LBB0_48:
	v_lshl_add_u64 v[12:13], v[8:9], 0, s[6:7]
	global_load_dwordx4 v[8:11], v[12:13], off nt
	v_mov_b32_e32 v72, 1.0
	s_and_b64 vcc, exec, s[4:5]
	v_mov_b32_e32 v74, 1.0
	s_cbranch_vccnz .LBB0_50
	global_load_dword v74, v[34:35], off offset:64
.LBB0_50:
	v_lshl_add_u64 v[16:17], v[12:13], 0, s[6:7]
	global_load_dwordx4 v[12:15], v[16:17], off nt
	s_and_b64 vcc, exec, s[4:5]
	s_cbranch_vccnz .LBB0_52
	global_load_dword v72, v[34:35], off offset:96
.LBB0_52:
	v_lshl_add_u64 v[20:21], v[16:17], 0, s[6:7]
	global_load_dwordx4 v[16:19], v[20:21], off nt
	v_mov_b32_e32 v76, 1.0
	s_and_b64 vcc, exec, s[4:5]
	v_mov_b32_e32 v78, 1.0
	s_cbranch_vccnz .LBB0_54
	global_load_dword v78, v[34:35], off offset:128
.LBB0_54:
	v_lshl_add_u64 v[24:25], v[20:21], 0, s[6:7]
	global_load_dwordx4 v[20:23], v[24:25], off nt
	s_and_b64 vcc, exec, s[4:5]
	s_cbranch_vccnz .LBB0_56
	global_load_dword v76, v[34:35], off offset:160
.LBB0_56:
	v_lshl_add_u64 v[28:29], v[24:25], 0, s[6:7]
	global_load_dwordx4 v[24:27], v[28:29], off nt
	v_mov_b32_e32 v80, 1.0
	s_and_b64 vcc, exec, s[4:5]
	v_mov_b32_e32 v82, 1.0
	s_cbranch_vccnz .LBB0_58
	global_load_dword v82, v[34:35], off offset:192
.LBB0_58:
	v_lshl_add_u64 v[28:29], v[28:29], 0, s[6:7]
	global_load_dwordx4 v[28:31], v[28:29], off nt
	s_and_b64 vcc, exec, s[4:5]
	s_cbranch_vccnz .LBB0_60
	global_load_dword v80, v[34:35], off offset:224

.LBB0_90:
	s_waitcnt vmcnt(5)
	v_add_u32_e32 v38, s51, v65
	v_ashrrev_i32_e32 v39, 31, v38
	v_mul_lo_u32 v34, s34, v39
	v_mul_lo_u32 v35, s35, v38
	v_mad_u64_u32 v[32:33], s[26:27], s34, v38, 0
	v_add3_u32 v33, v33, v34, v35
	v_lshl_add_u64 v[32:33], v[32:33], 2, s[28:29]
	s_ashr_i32 s37, s36, 31
	v_lshl_add_u64 v[32:33], s[36:37], 2, v[32:33]
	v_lshl_add_u64 v[36:37], v[66:67], 2, v[32:33]
	global_load_dwordx4 v[32:35], v[36:37], off nt
	s_cmp_lg_u64 s[4:5], 0
	v_mov_b32_e32 v73, 1.0
	s_cselect_b64 s[28:29], -1, 0
	s_cmp_eq_u64 s[4:5], 0
	s_waitcnt vmcnt(1)
	v_lshl_add_u64 v[60:61], v[38:39], 2, s[4:5]
	v_mov_b32_e32 v75, 1.0
	v_mov_b32_e32 v77, 1.0
	s_cbranch_scc1 .LBB0_92
	global_load_dword v75, v[60:61], off
	global_load_dword v77, v[60:61], off offset:32
.LBB0_92:
	s_lshl_b64 s[26:27], s[34:35], 5
	v_lshl_add_u64 v[46:47], v[36:37], 0, s[26:27]
	v_lshl_add_u64 v[44:45], v[46:47], 0, s[26:27]
	global_load_dwordx4 v[40:43], v[46:47], off nt
	global_load_dwordx4 v[36:39], v[44:45], off nt
	v_cndmask_b32_e64 v46, 0, 1, s[28:29]
	v_cmp_ne_u32_e64 s[4:5], 1, v46
	s_andn2_b64 vcc, exec, s[28:29]
	v_mov_b32_e32 v79, 1.0
	s_cbranch_vccnz .LBB0_94
	global_load_dword v73, v[60:61], off offset:64
	global_load_dword v79, v[60:61], off offset:96
.LBB0_94:
	v_lshl_add_u64 v[54:55], v[44:45], 0, s[26:27]
	v_lshl_add_u64 v[52:53], v[54:55], 0, s[26:27]
	global_load_dwordx4 v[48:51], v[54:55], off nt
	global_load_dwordx4 v[44:47], v[52:53], off nt
	v_mov_b32_e32 v81, 1.0
	s_and_b64 vcc, exec, s[4:5]
	v_mov_b32_e32 v83, 1.0
	v_mov_b32_e32 v86, 1.0
	s_cbranch_vccnz .LBB0_96
	global_load_dword v83, v[60:61], off offset:128
	global_load_dword v86, v[60:61], off offset:160
.LBB0_96:
	v_lshl_add_u64 v[88:89], v[52:53], 0, s[26:27]
	v_lshl_add_u64 v[62:63], v[88:89], 0, s[26:27]
	global_load_dwordx4 v[56:59], v[88:89], off nt
	global_load_dwordx4 v[52:55], v[62:63], off nt
	s_and_b64 vcc, exec, s[4:5]
	v_mov_b32_e32 v87, 1.0
	s_cbranch_vccnz .LBB0_98
	global_load_dword v81, v[60:61], off offset:192
	global_load_dword v87, v[60:61], off offset:224
.LBB0_98:
	v_lshl_add_u64 v[60:61], v[62:63], 0, s[26:27]
	global_load_dwordx4 v[60:63], v[60:61], off nt
	s_mov_b64 s[26:27], -1
	s_andn2_b64 vcc, exec, s[14:15]
	s_cbranch_vccnz .LBB0_70
.LBB0_99:
	s_waitcnt vmcnt(7)
	v_pk_mul_f32 v[88:89], v[70:71], v[0:1] op_sel_hi:[0,1]
	ds_write2_b32 v71, v88, v89 offset1:1
	v_pk_mul_f32 v[88:89], v[70:71], v[2:3] op_sel_hi:[0,1]
	ds_write2_b32 v71, v88, v89 offset0:2 offset1:3
	s_waitcnt vmcnt(6)
	v_pk_mul_f32 v[88:89], v[68:69], v[4:5] op_sel_hi:[0,1]
	v_add_u32_e32 v90, 0x420, v71
	ds_write2_b32 v90, v88, v89 offset1:1
	v_pk_mul_f32 v[88:89], v[68:69], v[6:7] op_sel_hi:[0,1]
	v_add_u32_e32 v90, 0x428, v71
	ds_write2_b32 v90, v88, v89 offset1:1
	s_waitcnt vmcnt(5)
	v_pk_mul_f32 v[88:89], v[74:75], v[8:9] op_sel_hi:[0,1]
	v_add_u32_e32 v90, 0x840, v71
	ds_write2_b32 v90, v88, v89 offset1:1
	v_pk_mul_f32 v[88:89], v[74:75], v[10:11] op_sel_hi:[0,1]
	v_add_u32_e32 v90, 0x848, v71
	ds_write2_b32 v90, v88, v89 offset1:1
	s_waitcnt vmcnt(4)
	v_pk_mul_f32 v[88:89], v[72:73], v[12:13] op_sel_hi:[0,1]
	v_add_u32_e32 v90, 0xc60, v71
	ds_write2_b32 v90, v88, v89 offset1:1
	v_pk_mul_f32 v[88:89], v[72:73], v[14:15] op_sel_hi:[0,1]
	v_add_u32_e32 v90, 0xc68, v71
	ds_write2_b32 v90, v88, v89 offset1:1
	s_waitcnt vmcnt(3)
	v_pk_mul_f32 v[88:89], v[78:79], v[16:17] op_sel_hi:[0,1]
	v_add_u32_e32 v90, 0x1080, v71
	ds_write2_b32 v90, v88, v89 offset1:1
	v_pk_mul_f32 v[88:89], v[78:79], v[18:19] op_sel_hi:[0,1]
	v_add_u32_e32 v90, 0x1088, v71
	ds_write2_b32 v90, v88, v89 offset1:1
	s_waitcnt vmcnt(2)
	v_pk_mul_f32 v[88:89], v[76:77], v[20:21] op_sel_hi:[0,1]
	v_add_u32_e32 v90, 0x14a0, v71
	ds_write2_b32 v90, v88, v89 offset1:1
	v_pk_mul_f32 v[88:89], v[76:77], v[22:23] op_sel_hi:[0,1]
	v_add_u32_e32 v90, 0x14a8, v71
	ds_write2_b32 v90, v88, v89 offset1:1
	s_waitcnt vmcnt(1)
	v_pk_mul_f32 v[88:89], v[82:83], v[24:25] op_sel_hi:[0,1]
	v_add_u32_e32 v90, 0x18c0, v71
	ds_write2_b32 v90, v88, v89 offset1:1
	v_pk_mul_f32 v[88:89], v[82:83], v[26:27] op_sel_hi:[0,1]
	v_add_u32_e32 v90, 0x18c8, v71
	ds_write2_b32 v90, v88, v89 offset1:1
	s_waitcnt vmcnt(0)
	v_pk_mul_f32 v[88:89], v[80:81], v[28:29] op_sel_hi:[0,1]
	v_add_u32_e32 v90, 0x1ce0, v71
	ds_write2_b32 v90, v88, v89 offset1:1
	v_pk_mul_f32 v[88:89], v[80:81], v[30:31] op_sel_hi:[0,1]
	v_add_u32_e32 v90, 0x1ce8, v71
	ds_write2_b32 v90, v88, v89 offset1:1
	s_waitcnt lgkmcnt(0)
	v_add_u32_e32 v112, s44, v65
	ds_read2_b32 v[92:93], v69 offset0:33 offset1:41
	ds_read2_b32 v[94:95], v69 offset1:8
	ds_read2_b32 v[96:97], v69 offset0:66 offset1:74
	ds_read2_b32 v[98:99], v69 offset0:99 offset1:107
	ds_read2_b32 v[100:101], v69 offset0:132 offset1:140
	ds_read2_b32 v[102:103], v69 offset0:165 offset1:173
	ds_read2_b32 v[104:105], v69 offset0:198 offset1:206
	ds_read2_b32 v[106:107], v69 offset0:231 offset1:239
	v_mad_u64_u32 v[108:109], s[4:5], s45, v112, 0
	s_waitcnt lgkmcnt(6)
	v_cvt_pk_bf16_f32 v88, v94, v92
	v_ashrrev_i32_e32 v94, 31, v112
	v_mov_b32_e32 v92, v109
	v_mad_u64_u32 v[110:111], s[4:5], s45, v94, v[92:93]
	v_mov_b32_e32 v109, v110
	s_ashr_i32 s13, s12, 31
	v_lshl_add_u64 v[108:109], v[108:109], 1, s[16:17]
	s_lshl_b64 s[4:5], s[12:13], 1
	v_lshl_add_u64 v[108:109], v[108:109], 0, s[4:5]
	s_waitcnt lgkmcnt(4)
	v_cvt_pk_bf16_f32 v89, v96, v98
	s_waitcnt lgkmcnt(2)
	v_cvt_pk_bf16_f32 v90, v100, v102
	s_waitcnt lgkmcnt(0)
	v_cvt_pk_bf16_f32 v91, v104, v106
	v_lshl_add_u64 v[108:109], v[108:109], 0, v[84:85]
	v_add_u32_e32 v92, 8, v112
	global_store_dwordx4 v[108:109], v[88:91], off sc1
	s_nop 1
	v_cvt_pk_bf16_f32 v88, v95, v93
	v_ashrrev_i32_e32 v95, 31, v92
	v_mad_u64_u32 v[92:93], s[28:29], s45, v92, 0
	v_mov_b32_e32 v94, v93
	v_mad_u64_u32 v[94:95], s[28:29], s45, v95, v[94:95]
	v_mov_b32_e32 v93, v94
	v_lshl_add_u64 v[92:93], v[92:93], 1, s[16:17]
	v_lshl_add_u64 v[92:93], v[92:93], 0, s[4:5]
	v_cvt_pk_bf16_f32 v89, v97, v99
	v_cvt_pk_bf16_f32 v90, v101, v103
	v_cvt_pk_bf16_f32 v91, v105, v107
	v_lshl_add_u64 v[92:93], v[92:93], 0, v[84:85]
	ds_read2_b32 v[94:95], v69 offset0:16 offset1:24
	ds_read2_b32 v[96:97], v69 offset0:49 offset1:57
	ds_read2_b32 v[98:99], v69 offset0:82 offset1:90
	ds_read2_b32 v[100:101], v69 offset0:115 offset1:123
	ds_read2_b32 v[102:103], v69 offset0:148 offset1:156
	ds_read2_b32 v[104:105], v69 offset0:181 offset1:189
	ds_read2_b32 v[106:107], v69 offset0:214 offset1:222
	ds_read2_b32 v[108:109], v69 offset0:247 offset1:255
	global_store_dwordx4 v[92:93], v[88:91], off sc1
	v_add_u32_e32 v92, 16, v112
	s_waitcnt lgkmcnt(6)
	v_cvt_pk_bf16_f32 v88, v94, v96
	v_ashrrev_i32_e32 v96, 31, v92
	v_mad_u64_u32 v[92:93], s[28:29], s45, v92, 0
	v_mov_b32_e32 v94, v93
	v_mad_u64_u32 v[110:111], s[28:29], s45, v96, v[94:95]
	v_mov_b32_e32 v93, v110
	v_lshl_add_u64 v[92:93], v[92:93], 1, s[16:17]
	v_lshl_add_u64 v[92:93], v[92:93], 0, s[4:5]
	s_waitcnt lgkmcnt(4)
	v_cvt_pk_bf16_f32 v89, v98, v100
	s_waitcnt lgkmcnt(2)
	v_cvt_pk_bf16_f32 v90, v102, v104
	s_waitcnt lgkmcnt(0)
	v_cvt_pk_bf16_f32 v91, v106, v108
	v_lshl_add_u64 v[92:93], v[92:93], 0, v[84:85]
	global_store_dwordx4 v[92:93], v[88:91], off sc1
	v_add_u32_e32 v92, 24, v112
	s_nop 0
	v_cvt_pk_bf16_f32 v88, v95, v97
	v_ashrrev_i32_e32 v95, 31, v92
	v_mad_u64_u32 v[92:93], s[28:29], s45, v92, 0
	v_mov_b32_e32 v94, v93
	v_mad_u64_u32 v[94:95], s[28:29], s45, v95, v[94:95]
	v_mov_b32_e32 v93, v94
	v_lshl_add_u64 v[92:93], v[92:93], 1, s[16:17]
	v_lshl_add_u64 v[92:93], v[92:93], 0, s[4:5]
	v_cvt_pk_bf16_f32 v89, v99, v101
	v_cvt_pk_bf16_f32 v90, v103, v105
	v_cvt_pk_bf16_f32 v91, v107, v109
	v_lshl_add_u64 v[92:93], v[92:93], 0, v[84:85]
	global_store_dwordx4 v[92:93], v[88:91], off sc1
	s_waitcnt lgkmcnt(0)
	s_andn2_b64 vcc, exec, s[24:25]
	s_cbranch_vccnz .LBB0_62

.LBB0_104:
	s_add_i32 s22, s16, s52
	s_cmpk_lt_i32 s22, 0x4000
	s_cselect_b64 s[18:19], -1, 0
	s_and_b64 s[6:7], s[18:19], exec
	s_cselect_b32 s14, s22, s16
	s_ashr_i32 s17, s16, 31
	s_lshl_b64 s[6:7], s[16:17], 12
	s_ashr_i32 s15, s14, 31
	s_lshl_b64 s[24:25], s[14:15], 12
	v_lshl_add_u64 v[36:37], v[34:35], 0, s[6:7]
	v_lshl_add_u64 v[38:39], v[34:35], 0, s[24:25]
	global_load_dwordx4 v[28:31], v[36:37], off nt
	global_load_dwordx4 v[20:23], v[36:37], off offset:1024 nt
	global_load_dwordx4 v[24:27], v[38:39], off nt
	global_load_dwordx4 v[16:19], v[38:39], off offset:1024 nt
	global_load_dwordx4 v[12:15], v[36:37], off offset:2048 nt
	global_load_dwordx4 v[4:7], v[36:37], off offset:3072 nt
	global_load_dwordx4 v[8:11], v[38:39], off offset:2048 nt
	s_waitcnt lgkmcnt(0)
	global_load_dwordx4 v[0:3], v[38:39], off offset:3072 nt
	s_lshl_b64 s[6:7], s[16:17], 11
	s_lshl_b64 s[24:25], s[14:15], 11
	v_lshl_add_u64 v[38:39], v[32:33], 0, s[6:7]
	s_cmpk_gt_i32 s22, 0x3fff
	v_lshl_add_u64 v[36:37], v[32:33], 0, s[24:25]
	s_waitcnt vmcnt(7)
	v_cvt_pk_bf16_f32 v54, v28, v29
	v_cvt_pk_bf16_f32 v55, v30, v31
	global_store_dwordx2 v[38:39], v[54:55], off
	s_cbranch_scc1 .LBB0_106
	s_waitcnt vmcnt(6)
	v_cvt_pk_bf16_f32 v54, v24, v25
	v_cvt_pk_bf16_f32 v55, v26, v27
	global_store_dwordx2 v[36:37], v[54:55], off

.LBB0_118:
	s_waitcnt lgkmcnt(0)
	global_load_dwordx4 v[12:15], v[2:3], off offset:-2048 nt
	v_lshl_add_u64 v[16:17], s[12:13], 0, v[0:1]
	s_waitcnt vmcnt(1)
	v_add_co_u32_e32 v28, vcc, s20, v16
	s_waitcnt vmcnt(0)
	v_cvt_pk_bf16_f32 v16, v12, v13
	v_addc_co_u32_e32 v29, vcc, 0, v17, vcc
	v_cvt_pk_bf16_f32 v17, v14, v15
	global_store_dwordx2 v[28:29], v[16:17], off
	global_load_dwordx4 v[16:19], v[2:3], off offset:-1024 nt
	v_mul_f32_e32 v11, v13, v13
	v_mul_f32_e32 v13, v15, v15
	v_fmac_f32_e32 v11, v12, v12
	v_fmac_f32_e32 v13, v14, v14
	v_add_f32_e32 v11, v11, v13
	s_waitcnt vmcnt(0)
	v_cvt_pk_bf16_f32 v20, v16, v17
	v_cvt_pk_bf16_f32 v21, v18, v19
	global_store_dwordx2 v[28:29], v[20:21], off offset:512
	global_load_dwordx4 v[20:23], v[2:3], off nt
	v_mul_f32_e32 v12, v17, v17
	v_mul_f32_e32 v13, v19, v19
	v_fmac_f32_e32 v12, v16, v16
	v_fmac_f32_e32 v13, v18, v18
	v_add_f32_e32 v12, v12, v13
	v_add_f32_e32 v11, v11, v12
	s_waitcnt vmcnt(0)
	v_cvt_pk_bf16_f32 v24, v20, v21
	v_cvt_pk_bf16_f32 v25, v22, v23
	global_store_dwordx2 v[28:29], v[24:25], off offset:1024
	global_load_dwordx4 v[24:27], v[2:3], off offset:1024 nt
	v_mul_f32_e32 v12, v21, v21
	v_mul_f32_e32 v13, v23, v23
	v_fmac_f32_e32 v12, v20, v20
	v_fmac_f32_e32 v13, v22, v22
	v_add_f32_e32 v12, v12, v13
	v_add_f32_e32 v11, v11, v12
	s_waitcnt vmcnt(0)
	v_mul_f32_e32 v12, v25, v25
	v_mul_f32_e32 v13, v27, v27
	v_fmac_f32_e32 v12, v24, v24
	v_fmac_f32_e32 v13, v26, v26
	v_add_f32_e32 v12, v12, v13
	v_add_f32_e32 v11, v11, v12
	ds_bpermute_b32 v12, v4, v11
	v_cvt_pk_bf16_f32 v14, v24, v25
	v_cvt_pk_bf16_f32 v15, v26, v27
	global_store_dwordx2 v[28:29], v[14:15], off offset:1536
	s_waitcnt lgkmcnt(0)
	v_add_f32_e32 v11, v11, v12
	ds_bpermute_b32 v12, v5, v11
	s_waitcnt lgkmcnt(0)
	v_add_f32_e32 v11, v11, v12
	ds_bpermute_b32 v12, v6, v11
	s_waitcnt lgkmcnt(0)
	v_add_f32_e32 v11, v11, v12
	ds_bpermute_b32 v12, v7, v11
	s_waitcnt lgkmcnt(0)
	v_add_f32_e32 v11, v11, v12
	ds_bpermute_b32 v12, v8, v11
	s_waitcnt lgkmcnt(0)
	v_add_f32_e32 v11, v11, v12
	ds_bpermute_b32 v12, v9, v11
	s_and_saveexec_b64 s[16:17], s[4:5]
	s_cbranch_execz .LBB0_117
	s_waitcnt lgkmcnt(0)
	v_add_f32_e32 v11, v11, v12
	v_mul_f32_e32 v11, 0x49800000, v11
	v_trunc_f32_e32 v11, v11
	v_mul_f32_e64 v12, |v11|, s21
	v_floor_f32_e32 v12, v12
	v_fma_f32 v13, v12, s22, |v11|
	v_cvt_u32_f32_e32 v12, v12
	v_cvt_u32_f32_e32 v13, v13
	v_ashrrev_i32_e32 v11, 31, v11
	s_add_u32 s24, s12, s18
	v_xor_b32_e32 v14, v12, v11
	v_xor_b32_e32 v12, v13, v11
	v_sub_co_u32_e32 v12, vcc, v12, v11
	s_addc_u32 s25, s13, s19
	s_nop 0
	v_subb_co_u32_e32 v13, vcc, v14, v11, vcc
	global_store_dwordx2 v10, v[12:13], s[24:25]
	s_branch .LBB0_117

.LBB0_543:
	s_waitcnt vmcnt(0)
	v_mov_b32_e32 v31, 0
	v_ashrrev_i32_e32 v65, 3, v198
	s_andn2_b64 vcc, exec, s[24:25]
	v_mov_b32_e32 v30, v31
	v_mov_b32_e32 v29, v31
	v_mov_b32_e32 v28, v31
	v_mov_b32_e32 v27, v31
	v_mov_b32_e32 v26, v31
	v_mov_b32_e32 v25, v31
	v_mov_b32_e32 v24, v31
	v_mov_b32_e32 v23, v31
	v_mov_b32_e32 v22, v31
	v_mov_b32_e32 v21, v31
	v_mov_b32_e32 v20, v31
	v_mov_b32_e32 v19, v31
	v_mov_b32_e32 v18, v31
	v_mov_b32_e32 v17, v31
	v_mov_b32_e32 v16, v31
	v_mov_b32_e32 v15, v31
	v_mov_b32_e32 v14, v31
	v_mov_b32_e32 v13, v31
	v_mov_b32_e32 v12, v31
	v_mov_b32_e32 v11, v31
	v_mov_b32_e32 v10, v31
	v_mov_b32_e32 v9, v31
	v_mov_b32_e32 v8, v31
	v_mov_b32_e32 v7, v31
	v_mov_b32_e32 v6, v31
	v_mov_b32_e32 v5, v31
	v_mov_b32_e32 v4, v31
	v_mov_b32_e32 v3, v31
	v_mov_b32_e32 v2, v31
	s_waitcnt lgkmcnt(0)
	v_mov_b32_e32 v1, v31
	v_mov_b32_e32 v0, v31
	s_cbranch_vccnz .LBB0_561
	v_add_u32_e32 v6, s6, v65
	v_ashrrev_i32_e32 v7, 31, v6
	v_mul_lo_u32 v2, s38, v7
	v_mul_lo_u32 v3, s39, v6
	v_mad_u64_u32 v[0:1], s[24:25], s38, v6, 0
	v_add3_u32 v1, v1, v2, v3
	v_lshl_add_u64 v[0:1], v[0:1], 2, s[42:43]
	s_ashr_i32 s35, s34, 31
	v_lshl_add_u64 v[0:1], s[34:35], 2, v[0:1]
	v_lshlrev_b32_e32 v158, 2, v32
	v_lshl_add_u64 v[4:5], v[0:1], 0, v[158:159]
	global_load_dwordx4 v[0:3], v[4:5], off nt
	s_cmp_lg_u64 s[40:41], 0
	v_mov_b32_e32 v64, 1.0
	s_cselect_b64 s[28:29], -1, 0
	s_cmp_eq_u64 s[40:41], 0
	v_lshl_add_u64 v[34:35], v[6:7], 2, s[40:41]
	v_mov_b32_e32 v66, 1.0
	s_cbranch_scc1 .LBB0_546
	global_load_dword v66, v[34:35], off
.LBB0_546:
	s_lshl_b64 s[24:25], s[38:39], 5
	v_lshl_add_u64 v[8:9], v[4:5], 0, s[24:25]
	global_load_dwordx4 v[4:7], v[8:9], off nt
	v_cndmask_b32_e64 v10, 0, 1, s[28:29]
	v_cmp_ne_u32_e64 s[38:39], 1, v10
	s_andn2_b64 vcc, exec, s[28:29]
	s_cbranch_vccnz .LBB0_548
	global_load_dword v64, v[34:35], off offset:32
.LBB0_548:
	v_lshl_add_u64 v[12:13], v[8:9], 0, s[24:25]
	global_load_dwordx4 v[8:11], v[12:13], off nt
	v_mov_b32_e32 v68, 1.0
	s_and_b64 vcc, exec, s[38:39]
	v_mov_b32_e32 v70, 1.0
	s_cbranch_vccnz .LBB0_550
	global_load_dword v70, v[34:35], off offset:64
.LBB0_550:
	v_lshl_add_u64 v[16:17], v[12:13], 0, s[24:25]
	global_load_dwordx4 v[12:15], v[16:17], off nt
	s_and_b64 vcc, exec, s[38:39]
	s_cbranch_vccnz .LBB0_552
	global_load_dword v68, v[34:35], off offset:96
.LBB0_552:
	v_lshl_add_u64 v[20:21], v[16:17], 0, s[24:25]
	global_load_dwordx4 v[16:19], v[20:21], off nt
	v_mov_b32_e32 v72, 1.0
	s_and_b64 vcc, exec, s[38:39]
	v_mov_b32_e32 v74, 1.0
	s_cbranch_vccnz .LBB0_554
	global_load_dword v74, v[34:35], off offset:128
.LBB0_554:
	v_lshl_add_u64 v[24:25], v[20:21], 0, s[24:25]
	global_load_dwordx4 v[20:23], v[24:25], off nt
	s_and_b64 vcc, exec, s[38:39]
	s_cbranch_vccnz .LBB0_556
	global_load_dword v72, v[34:35], off offset:160
.LBB0_556:
	v_lshl_add_u64 v[28:29], v[24:25], 0, s[24:25]
	global_load_dwordx4 v[24:27], v[28:29], off nt
	v_mov_b32_e32 v76, 1.0
	s_and_b64 vcc, exec, s[38:39]
	v_mov_b32_e32 v78, 1.0
	s_cbranch_vccnz .LBB0_558
	global_load_dword v78, v[34:35], off offset:192
.LBB0_558:
	v_lshl_add_u64 v[28:29], v[28:29], 0, s[24:25]
	global_load_dwordx4 v[28:31], v[28:29], off nt
	s_and_b64 vcc, exec, s[38:39]
	s_cbranch_vccnz .LBB0_560
	global_load_dword v76, v[34:35], off offset:224

.LBB0_598:
	s_waitcnt vmcnt(0)
	v_add_u32_e32 v60, s85, v65
	v_ashrrev_i32_e32 v61, 31, v60
	v_mul_lo_u32 v34, s50, v61
	v_mul_lo_u32 v35, s51, v60
	v_mad_u64_u32 v[32:33], s[38:39], s50, v60, 0
	v_add3_u32 v33, v33, v34, v35
	s_waitcnt lgkmcnt(0)
	v_lshl_add_u64 v[32:33], v[32:33], 2, s[42:43]
	s_ashr_i32 s61, s60, 31
	v_lshl_add_u64 v[32:33], s[60:61], 2, v[32:33]
	v_lshl_add_u64 v[36:37], v[80:81], 2, v[32:33]
	global_load_dwordx4 v[32:35], v[36:37], off nt
	s_cmp_lg_u64 s[40:41], 0
	v_mov_b32_e32 v77, 1.0
	s_cselect_b64 s[48:49], -1, 0
	s_cmp_eq_u64 s[40:41], 0
	v_mov_b32_e32 v79, 1.0
	v_mov_b32_e32 v82, 1.0
	s_cbranch_scc1 .LBB0_600
	v_add_u32_e32 v38, s85, v67
	v_ashrrev_i32_e32 v39, 31, v38
	v_lshl_add_u64 v[40:41], v[60:61], 2, s[40:41]
	v_lshl_add_u64 v[38:39], v[38:39], 2, s[40:41]
	global_load_dword v79, v[40:41], off
	global_load_dword v82, v[38:39], off
.LBB0_600:
	s_lshl_b64 s[42:43], s[50:51], 5
	v_lshl_add_u64 v[36:37], v[36:37], 0, s[42:43]
	v_lshl_add_u64 v[44:45], v[36:37], 0, s[42:43]
	global_load_dwordx4 v[40:43], v[36:37], off nt
	s_nop 0
	global_load_dwordx4 v[36:39], v[44:45], off nt
	v_cndmask_b32_e64 v46, 0, 1, s[48:49]
	v_cmp_ne_u32_e64 s[38:39], 1, v46
	s_andn2_b64 vcc, exec, s[48:49]
	v_mov_b32_e32 v83, 1.0
	s_cbranch_vccnz .LBB0_602
	v_add_u32_e32 v48, s85, v69
	v_add_u32_e32 v46, s85, v71
	v_ashrrev_i32_e32 v49, 31, v48
	v_ashrrev_i32_e32 v47, 31, v46
	v_lshl_add_u64 v[48:49], v[48:49], 2, s[40:41]
	v_lshl_add_u64 v[46:47], v[46:47], 2, s[40:41]
	global_load_dword v77, v[48:49], off
	global_load_dword v83, v[46:47], off
.LBB0_602:
	v_lshl_add_u64 v[44:45], v[44:45], 0, s[42:43]
	v_lshl_add_u64 v[52:53], v[44:45], 0, s[42:43]
	global_load_dwordx4 v[48:51], v[44:45], off nt
	s_nop 0
	global_load_dwordx4 v[44:47], v[52:53], off nt
	v_mov_b32_e32 v84, 1.0
	s_and_b64 vcc, exec, s[38:39]
	v_mov_b32_e32 v85, 1.0
	v_mov_b32_e32 v86, 1.0
	s_cbranch_vccnz .LBB0_604
	v_add_u32_e32 v56, 32, v60
	v_add_u32_e32 v54, 40, v60
	v_ashrrev_i32_e32 v57, 31, v56
	v_ashrrev_i32_e32 v55, 31, v54
	v_lshl_add_u64 v[56:57], v[56:57], 2, s[40:41]
	v_lshl_add_u64 v[54:55], v[54:55], 2, s[40:41]
	global_load_dword v85, v[56:57], off
	global_load_dword v86, v[54:55], off
.LBB0_604:
	v_lshl_add_u64 v[52:53], v[52:53], 0, s[42:43]
	v_lshl_add_u64 v[62:63], v[52:53], 0, s[42:43]
	global_load_dwordx4 v[56:59], v[52:53], off nt
	s_nop 0
	global_load_dwordx4 v[52:55], v[62:63], off nt
	s_and_b64 vcc, exec, s[38:39]
	v_mov_b32_e32 v87, 1.0
	s_cbranch_vccnz .LBB0_606
	v_add_u32_e32 v88, 56, v60
	v_add_u32_e32 v60, 48, v60
	v_ashrrev_i32_e32 v61, 31, v60
	v_ashrrev_i32_e32 v89, 31, v88
	v_lshl_add_u64 v[60:61], v[60:61], 2, s[40:41]
	v_lshl_add_u64 v[88:89], v[88:89], 2, s[40:41]
	global_load_dword v84, v[60:61], off
	global_load_dword v87, v[88:89], off
.LBB0_606:
	v_lshl_add_u64 v[60:61], v[62:63], 0, s[42:43]
	global_load_dwordx4 v[60:63], v[60:61], off nt
	s_mov_b64 s[38:39], -1
	s_andn2_b64 vcc, exec, s[12:13]
	s_cbranch_vccnz .LBB0_575
.LBB0_607:
	s_waitcnt vmcnt(7)
	v_pk_mul_f32 v[88:89], v[66:67], v[0:1] op_sel_hi:[0,1]
	ds_write2_b32 v75, v88, v89 offset1:1
	v_pk_mul_f32 v[88:89], v[66:67], v[2:3] op_sel_hi:[0,1]
	ds_write2_b32 v75, v88, v89 offset0:2 offset1:3
	s_waitcnt vmcnt(6)
	v_pk_mul_f32 v[88:89], v[64:65], v[4:5] op_sel_hi:[0,1]
	v_add_u32_e32 v90, 0x420, v75
	ds_write2_b32 v90, v88, v89 offset1:1
	v_pk_mul_f32 v[88:89], v[64:65], v[6:7] op_sel_hi:[0,1]
	v_add_u32_e32 v90, 0x428, v75
	ds_write2_b32 v90, v88, v89 offset1:1
	s_waitcnt vmcnt(5)
	v_pk_mul_f32 v[88:89], v[70:71], v[8:9] op_sel_hi:[0,1]
	v_add_u32_e32 v90, 0x840, v75
	ds_write2_b32 v90, v88, v89 offset1:1
	v_pk_mul_f32 v[88:89], v[70:71], v[10:11] op_sel_hi:[0,1]
	v_add_u32_e32 v90, 0x848, v75
	ds_write2_b32 v90, v88, v89 offset1:1
	s_waitcnt vmcnt(4)
	v_pk_mul_f32 v[88:89], v[68:69], v[12:13] op_sel_hi:[0,1]
	v_add_u32_e32 v90, 0xc60, v75
	ds_write2_b32 v90, v88, v89 offset1:1
	v_pk_mul_f32 v[88:89], v[68:69], v[14:15] op_sel_hi:[0,1]
	v_add_u32_e32 v90, 0xc68, v75
	ds_write2_b32 v90, v88, v89 offset1:1
	s_waitcnt vmcnt(3)
	v_pk_mul_f32 v[88:89], v[74:75], v[16:17] op_sel_hi:[0,1]
	v_add_u32_e32 v90, 0x1080, v75
	ds_write2_b32 v90, v88, v89 offset1:1
	v_pk_mul_f32 v[88:89], v[74:75], v[18:19] op_sel_hi:[0,1]
	v_add_u32_e32 v90, 0x1088, v75
	ds_write2_b32 v90, v88, v89 offset1:1
	s_waitcnt vmcnt(2)
	v_pk_mul_f32 v[88:89], v[72:73], v[20:21] op_sel_hi:[0,1]
	v_add_u32_e32 v90, 0x14a0, v75
	ds_write2_b32 v90, v88, v89 offset1:1
	v_pk_mul_f32 v[88:89], v[72:73], v[22:23] op_sel_hi:[0,1]
	v_add_u32_e32 v90, 0x14a8, v75
	ds_write2_b32 v90, v88, v89 offset1:1
	s_waitcnt vmcnt(1)
	v_pk_mul_f32 v[88:89], v[78:79], v[24:25] op_sel_hi:[0,1]
	v_add_u32_e32 v90, 0x18c0, v75
	ds_write2_b32 v90, v88, v89 offset1:1
	v_pk_mul_f32 v[88:89], v[78:79], v[26:27] op_sel_hi:[0,1]
	v_add_u32_e32 v90, 0x18c8, v75
	ds_write2_b32 v90, v88, v89 offset1:1
	s_waitcnt vmcnt(0)
	v_pk_mul_f32 v[88:89], v[76:77], v[28:29] op_sel_hi:[0,1]
	v_add_u32_e32 v90, 0x1ce0, v75
	ds_write2_b32 v90, v88, v89 offset1:1
	v_pk_mul_f32 v[88:89], v[76:77], v[30:31] op_sel_hi:[0,1]
	v_add_u32_e32 v90, 0x1ce8, v75
	ds_write2_b32 v90, v88, v89 offset1:1
	s_waitcnt lgkmcnt(0)
	ds_read2_b32 v[92:93], v73 offset0:33 offset1:41
	ds_read2_b32 v[94:95], v73 offset1:8
	ds_read2_b32 v[96:97], v73 offset0:66 offset1:74
	ds_read2_b32 v[98:99], v73 offset0:99 offset1:107
	ds_read2_b32 v[100:101], v73 offset0:132 offset1:140
	ds_read2_b32 v[102:103], v73 offset0:165 offset1:173
	ds_read2_b32 v[104:105], v73 offset0:198 offset1:206
	ds_read2_b32 v[106:107], v73 offset0:231 offset1:239
	s_waitcnt lgkmcnt(0)
	v_cvt_pk_bf16_f32 v88, v94, v92
	v_add_u32_e32 v92, s81, v65
	v_mad_u64_u32 v[108:109], s[40:41], s82, v92, 0
	v_ashrrev_i32_e32 v94, 31, v92
	v_mov_b32_e32 v92, v109
	v_mad_u64_u32 v[110:111], s[40:41], s82, v94, v[92:93]
	v_mov_b32_e32 v109, v110
	s_ashr_i32 s7, s6, 31
	v_lshl_add_u64 v[108:109], v[108:109], 1, s[16:17]
	s_lshl_b64 s[40:41], s[6:7], 1
	v_lshl_add_u64 v[108:109], v[108:109], 0, s[40:41]
	v_cvt_pk_bf16_f32 v89, v96, v98
	v_cvt_pk_bf16_f32 v90, v100, v102
	v_cvt_pk_bf16_f32 v91, v104, v106
	v_lshl_add_u64 v[108:109], v[108:109], 0, v[158:159]
	v_add_u32_e32 v92, s81, v67
	global_store_dwordx4 v[108:109], v[88:91], off sc1
	s_nop 1
	v_cvt_pk_bf16_f32 v88, v95, v93
	v_ashrrev_i32_e32 v95, 31, v92
	v_mad_u64_u32 v[92:93], s[42:43], s82, v92, 0
	v_mov_b32_e32 v94, v93
	v_mad_u64_u32 v[94:95], s[42:43], s82, v95, v[94:95]
	v_mov_b32_e32 v93, v94
	v_lshl_add_u64 v[92:93], v[92:93], 1, s[16:17]
	v_lshl_add_u64 v[92:93], v[92:93], 0, s[40:41]
	v_cvt_pk_bf16_f32 v89, v97, v99
	v_cvt_pk_bf16_f32 v90, v101, v103
	v_cvt_pk_bf16_f32 v91, v105, v107
	v_lshl_add_u64 v[92:93], v[92:93], 0, v[158:159]
	ds_read2_b32 v[94:95], v73 offset0:16 offset1:24
	ds_read2_b32 v[96:97], v73 offset0:49 offset1:57
	ds_read2_b32 v[98:99], v73 offset0:82 offset1:90
	ds_read2_b32 v[100:101], v73 offset0:115 offset1:123
	ds_read2_b32 v[102:103], v73 offset0:148 offset1:156
	ds_read2_b32 v[104:105], v73 offset0:181 offset1:189
	ds_read2_b32 v[106:107], v73 offset0:214 offset1:222
	ds_read2_b32 v[108:109], v73 offset0:247 offset1:255
	global_store_dwordx4 v[92:93], v[88:91], off sc1
	v_add_u32_e32 v92, s81, v69
	s_waitcnt lgkmcnt(6)
	v_cvt_pk_bf16_f32 v88, v94, v96
	v_ashrrev_i32_e32 v96, 31, v92
	v_mad_u64_u32 v[92:93], s[42:43], s82, v92, 0
	v_mov_b32_e32 v94, v93
	v_mad_u64_u32 v[110:111], s[42:43], s82, v96, v[94:95]
	v_mov_b32_e32 v93, v110
	v_lshl_add_u64 v[92:93], v[92:93], 1, s[16:17]
	v_lshl_add_u64 v[92:93], v[92:93], 0, s[40:41]
	s_waitcnt lgkmcnt(4)
	v_cvt_pk_bf16_f32 v89, v98, v100
	s_waitcnt lgkmcnt(2)
	v_cvt_pk_bf16_f32 v90, v102, v104
	s_waitcnt lgkmcnt(0)
	v_cvt_pk_bf16_f32 v91, v106, v108
	v_lshl_add_u64 v[92:93], v[92:93], 0, v[158:159]
	global_store_dwordx4 v[92:93], v[88:91], off sc1
	v_add_u32_e32 v92, s81, v71
	s_nop 0
	v_cvt_pk_bf16_f32 v88, v95, v97
	v_ashrrev_i32_e32 v95, 31, v92
	v_mad_u64_u32 v[92:93], s[42:43], s82, v92, 0
	v_mov_b32_e32 v94, v93
	v_mad_u64_u32 v[94:95], s[42:43], s82, v95, v[94:95]
	v_mov_b32_e32 v93, v94
	v_lshl_add_u64 v[92:93], v[92:93], 1, s[16:17]
	v_lshl_add_u64 v[92:93], v[92:93], 0, s[40:41]
	v_cvt_pk_bf16_f32 v89, v99, v101
	v_cvt_pk_bf16_f32 v90, v103, v105
	v_cvt_pk_bf16_f32 v91, v107, v109
	v_lshl_add_u64 v[92:93], v[92:93], 0, v[158:159]
	global_store_dwordx4 v[92:93], v[88:91], off sc1
	s_waitcnt lgkmcnt(0)
	s_andn2_b64 vcc, exec, s[44:45]
	s_cbranch_vccnz .LBB0_562
